# scan loop: counted waits no longer cover the iteration's own O2 stores (vmcnt 1->2, 0->2, 6->8, first iteration peeled with one vmcnt(0))
# speedup vs baseline: 1.0027x; 1.0027x over previous
.LBB0_349:
	s_or_b64 exec, exec, s[0:1]
	s_ashr_i32 s0, s2, 4
	s_ashr_i32 s1, s0, 31
	s_waitcnt vmcnt(0)
	v_lshrrev_b32_e32 v13, 3, v143
	s_lshl_b64 s[0:1], s[0:1], 23
	s_ashr_i32 s3, s2, 31
	v_lshl_or_b32 v130, v13, 12, s0
	v_mov_b32_e32 v131, s1
	v_lshl_add_u64 v[2:3], s[4:5], 0, v[130:131]
	s_mov_b32 s1, 0
	s_lshl_b32 s0, s30, 1
	s_lshl_b64 s[10:11], s[2:3], 19
	v_lshl_add_u64 v[2:3], v[2:3], 0, s[0:1]
	s_add_u32 s0, s97, s10
	s_addc_u32 s1, s33, s11
	v_mov_b32_e32 v11, 0
	s_add_u32 s4, s70, s10
	v_lshlrev_b32_e32 v134, 4, v143
	s_addc_u32 s5, s71, s11
	v_mov_b32_e32 v135, v11
	v_lshl_add_u64 v[4:5], s[4:5], 0, v[134:135]
	s_mov_b32 s4, 0xe000000
	v_and_b32_e32 v38, 7, v143
	v_add_co_u32_e32 v6, vcc, s4, v4
	v_lshlrev_b32_e32 v10, 5, v38
	s_nop 0
	v_addc_co_u32_e32 v7, vcc, 0, v5, vcc
	s_brev_b32 s4, 8
	v_lshl_add_u64 v[2:3], v[2:3], 0, v[10:11]
	v_add_co_u32_e32 v8, vcc, s4, v4
	global_load_dwordx4 v[14:17], v[2:3], off offset:16
	global_load_dwordx4 v[26:29], v[2:3], off
	v_lshl_add_u64 v[2:3], s[0:1], 0, v[134:135]
	v_addc_co_u32_e32 v9, vcc, 0, v5, vcc
	s_movk_i32 s4, 0x2000
	v_add_co_u32_e32 v2, vcc, s4, v2
	s_mov_b32 s4, 0xe002000
	s_nop 0
	v_addc_co_u32_e32 v3, vcc, 0, v3, vcc
	global_load_dwordx4 v[18:21], v[6:7], off
	global_load_dwordx4 v[22:25], v[8:9], off
	v_add_co_u32_e32 v6, vcc, s4, v4
	s_mov_b32 s4, 0x10002000
	s_nop 0
	v_addc_co_u32_e32 v7, vcc, 0, v5, vcc
	s_lshl_b64 s[22:23], s[2:3], 15
	global_load_dwordx4 v[30:33], v[2:3], off
	global_load_dwordx4 v[66:69], v[6:7], off
	v_add_co_u32_e32 v2, vcc, s4, v4
	s_add_u32 s4, s70, s22
	s_nop 0
	v_addc_co_u32_e32 v3, vcc, 0, v5, vcc
	s_addc_u32 s5, s71, s23
	v_lshlrev_b32_e32 v4, 4, v142
	v_mov_b32_e32 v5, v11
	v_lshl_add_u64 v[6:7], s[4:5], 0, v[4:5]
	s_mov_b32 s4, 0x17200000
	s_lshl_b64 s[24:25], s[2:3], 17
	v_add_co_u32_e32 v6, vcc, s4, v6
	s_add_u32 s4, s50, s24
	s_nop 0
	v_addc_co_u32_e32 v7, vcc, 0, v7, vcc
	global_load_dwordx4 v[78:81], v[2:3], off
	global_load_dwordx4 v[74:77], v[6:7], off
	s_addc_u32 s5, s51, s25
	v_and_b32_e32 v2, 0xff0, v134
	global_load_dwordx4 v[34:37], v134, s[0:1]
	global_load_dwordx4 v[70:73], v2, s[4:5]
	v_and_b32_e32 v1, 0xf0, v134
	s_lshr_b32 s12, s12, 2
	v_and_b32_e32 v12, 15, v143
	v_add_u32_e32 v5, 0, v1
	v_and_b32_e32 v1, 0x70, v134
	s_and_b32 s12, s12, 0x3ffffff0
	v_add_u32_e32 v6, 0, v1
	v_or_b32_e32 v1, s12, v12
	s_movk_i32 s13, 0x90
	v_lshrrev_b32_e32 v133, 4, v142
	v_mul_lo_u32 v3, v1, s13
	v_add_u32_e32 v161, 0, v3
	v_lshlrev_b32_e32 v3, 2, v133
	v_or_b32_e32 v7, s12, v3
	s_add_i32 s12, 0, 0x11c00
	s_movk_i32 s13, 0x210
	v_mov_b32_e32 v8, s12
	v_or_b32_e32 v42, 32, v12
	v_mad_u32_u24 v9, v13, s13, v8
	v_add_u32_e32 v39, 0x200, v143
	v_mul_u32_u24_e32 v41, 0x110, v12
	v_mul_u32_u24_e32 v167, 0x90, v12
	v_or_b32_e32 v153, 16, v3
	v_or_b32_e32 v152, 32, v3
	v_or_b32_e32 v151, 48, v3
	v_or_b32_e32 v150, 64, v3
	v_or_b32_e32 v149, 0x50, v3
	v_or_b32_e32 v148, 0x60, v3
	v_or_b32_e32 v135, 0x70, v3
	v_mad_u32_u24 v12, v12, s13, v8
	v_mad_u32_u24 v8, v42, s13, v8
	v_or_b32_e32 v2, s24, v2
	v_mov_b32_e32 v3, s25
	s_mov_b64 s[12:13], 0x16a01000
	v_lshlrev_b32_e32 v132, 4, v38
	v_lshlrev_b32_e32 v163, 3, v133
	v_lshlrev_b32_e32 v165, 6, v38
	v_lshrrev_b32_e32 v38, 4, v143
	v_lshrrev_b32_e32 v40, 4, v39
	v_lshrrev_b32_e32 v39, 3, v39
	v_lshlrev_b32_e32 v175, 1, v152
	v_lshl_add_u64 v[136:137], v[2:3], 0, s[12:13]
	v_or_b32_e32 v2, s22, v4
	v_mov_b32_e32 v3, s23
	s_mov_b64 s[12:13], 0x17200400
	v_or_b32_e32 v140, s10, v134
	s_and_b32 s10, s2, 15
	s_movk_i32 s0, 0x100
	v_add_u32_e32 v164, 0, v163
	v_lshlrev_b32_e32 v7, 2, v7
	v_mul_u32_u24_e32 v38, 0x110, v38
	v_mul_u32_u24_e32 v13, 0x90, v13
	v_mul_u32_u24_e32 v40, 0x110, v40
	v_mul_u32_u24_e32 v39, 0x90, v39
	v_mul_u32_u24_e32 v43, 0x110, v42
	v_add_u32_e32 v44, 0, v175
	v_lshl_add_u64 v[138:139], v[2:3], 0, s[12:13]
	s_lshl_b32 s10, s10, 8
	v_mbcnt_lo_u32_b32 v2, -1, 0
	v_cmp_gt_u32_e64 s[4:5], 64, v143
	v_cmp_gt_u32_e64 s[0:1], s0, v143
	v_lshlrev_b32_e32 v162, 3, v142
	v_and_b32_e32 v166, 48, v143
	v_lshlrev_b32_e32 v168, 2, v153
	v_lshlrev_b32_e32 v169, 2, v152
	v_lshlrev_b32_e32 v170, 2, v151
	v_lshlrev_b32_e32 v171, 2, v150
	v_lshlrev_b32_e32 v172, 2, v149
	v_lshlrev_b32_e32 v173, 2, v148
	v_lshlrev_b32_e32 v174, 2, v135
	v_mov_b32_e32 v141, s11
	v_or3_b32 v144, v130, s10, v10
	v_mov_b32_e32 v145, v131
	s_mov_b32 s31, 31
	s_mov_b64 s[10:11], 0x1ae40000
	s_add_i32 s34, 0, 0x11a00
	v_mbcnt_hi_u32_b32 v177, -1, v2
	v_mov_b32_e32 v178, 0x358637bd
	s_mov_b32 s35, 0x800000
	s_mov_b32 s36, 0x12600000
	s_mov_b64 s[12:13], 0x1000
	s_mov_b64 s[22:23], 0x400
	s_mov_b64 s[24:25], 0x4000
	s_mov_b64 s[26:27], 0x40000
	v_add_u32_e32 v182, v5, v38
	v_add_u32_e32 v180, v6, v13
	v_add_u32_e32 v181, v5, v40
	v_add_u32_e32 v179, v6, v39
	v_add_u32_e32 v157, v164, v41
	v_add_u32_e32 v159, v12, v7
	v_add_u32_e32 v158, v164, v43
	v_add_u32_e32 v156, v44, v167
	v_add_u32_e32 v155, v8, v7
	v_add_u32_e32 v154, v9, v165
	v_mov_b32_e32 v10, v11
	v_mov_b32_e32 v12, v11
	v_mov_b32_e32 v13, v11
	v_mov_b32_e32 v38, v11
	v_mov_b32_e32 v39, v11
	v_mov_b32_e32 v40, v11
	v_mov_b32_e32 v41, v11
	v_mov_b32_e32 v42, v11
	v_mov_b32_e32 v43, v11
	v_mov_b32_e32 v44, v11
	v_mov_b32_e32 v45, v11
	v_mov_b32_e32 v46, v11
	v_mov_b32_e32 v47, v11
	v_mov_b32_e32 v48, v11
	v_mov_b32_e32 v49, v11
	v_mov_b32_e32 v50, v11
	v_mov_b32_e32 v51, v11
	v_mov_b32_e32 v52, v11
	v_mov_b32_e32 v53, v11
	v_mov_b32_e32 v54, v11
	v_mov_b32_e32 v55, v11
	v_mov_b32_e32 v56, v11
	v_mov_b32_e32 v57, v11
	v_mov_b32_e32 v62, v11
	v_mov_b32_e32 v63, v11
	v_mov_b32_e32 v64, v11
	v_mov_b32_e32 v65, v11
	v_mov_b32_e32 v58, v11
	v_mov_b32_e32 v59, v11
	v_mov_b32_e32 v60, v11
	v_mov_b32_e32 v61, v11
	s_waitcnt vmcnt(0)
.LBB0_350:
	v_add_u32_e32 v185, 0, v134
	s_waitcnt vmcnt(2)
	v_readfirstlane_b32 vcc_lo, v236
	s_mov_b32 vcc_hi, 0
	s_cmp_lg_u32 vcc_lo, 0
	s_cbranch_scc1 .Lscan_fok

.Lscan_fok:
	ds_write_b128 v182, v[34:37]
	ds_write_b128 v180, v[18:21] offset:34816
	ds_write_b128 v180, v[22:25] offset:53248
	ds_write_b128 v181, v[30:33]
	ds_write_b128 v179, v[66:69] offset:34816
	ds_write_b128 v179, v[78:81] offset:53248
	s_and_saveexec_b64 s[28:29], s[4:5]
	v_add_u32_e32 v2, 0x11800, v185
	ds_write_b128 v2, v[74:77]
	s_or_b64 exec, exec, s[28:29]
	s_and_saveexec_b64 s[28:29], s[0:1]
	s_cbranch_execz .LBB0_354
	s_waitcnt vmcnt(2)
	ds_write_b128 v185, v[70:73] offset:17408
.LBB0_354:
	s_or_b64 exec, exec, s[28:29]
	v_lshl_add_u64 v[146:147], s[70:71], 0, v[144:145]
	v_add_co_u32_e32 v4, vcc, 0x1ae40000, v146
	v_lshl_add_u64 v[66:67], s[70:71], 0, v[140:141]
	s_nop 0
	v_addc_co_u32_e32 v5, vcc, 0, v147, vcc
	v_add_co_u32_e32 v18, vcc, 0xc004000, v66
	s_waitcnt lgkmcnt(0)
	s_barrier
	s_nop 0
	v_addc_co_u32_e32 v19, vcc, 0, v67, vcc
	v_add_co_u32_e32 v20, vcc, 0xe004000, v66
	v_lshl_add_u64 v[2:3], v[146:147], 0, s[10:11]
	s_nop 0
	v_addc_co_u32_e32 v21, vcc, 0, v67, vcc
	v_add_co_u32_e32 v22, vcc, 0x10004000, v66
	v_add_u32_e32 v160, 0, v162
	s_nop 0
	v_addc_co_u32_e32 v23, vcc, 0, v67, vcc
	v_add_co_u32_e32 v30, vcc, 0xc006000, v66
	global_load_dwordx4 v[6:9], v[4:5], off
	s_nop 0
	global_load_dwordx4 v[2:5], v[2:3], off offset:16
	v_addc_co_u32_e32 v31, vcc, 0, v67, vcc
	global_load_dwordx4 v[34:37], v[18:19], off
	s_nop 0
	global_load_dwordx4 v[18:21], v[20:21], off
	s_nop 0
	global_load_dwordx4 v[22:25], v[22:23], off
	s_nop 0
	global_load_dwordx4 v[30:33], v[30:31], off
	ds_read2st64_b64 v[78:81], v160 offset0:34 offset1:35
	s_waitcnt vmcnt(8)
	ds_read2st64_b64 v[70:73], v160 offset0:36 offset1:37
	v_add_co_u32_e32 v118, vcc, 0xe006000, v66
	v_add_u32_e32 v176, v164, v167
	s_nop 0
	v_addc_co_u32_e32 v119, vcc, 0, v67, vcc
	v_add_u32_e32 v187, v161, v163
	s_waitcnt lgkmcnt(0)
	v_mov_b32_e32 v116, v70
	s_add_i32 s28, 0, 0x11800
	v_add_u32_e32 v70, 0x8800, v176
	v_add_co_u32_e32 v120, vcc, 0x10006000, v66
	v_add_u32_e32 v66, 0xd000, v187
	v_add_u32_e32 v189, s28, v166
	ds_read2_b64 v[82:85], v70 offset1:4
	v_add_u32_e32 v70, 0x9000, v176
	v_addc_co_u32_e32 v121, vcc, 0, v67, vcc
	ds_read2_b64 v[74:77], v66 offset1:4
	ds_read2_b64 v[66:69], v157 offset1:4
	v_add_u32_e32 v191, s28, v168
	ds_read_b128 v[86:89], v189
	ds_read_b128 v[90:93], v191
	ds_read2_b64 v[94:97], v70 offset0:32 offset1:36
	v_add_u32_e32 v70, 0x9800, v176
	ds_read2_b64 v[102:105], v70 offset0:64 offset1:68
	v_add_u32_e32 v190, s28, v169
	v_add_u32_e32 v70, 0xa000, v176
	v_add_u32_e32 v193, s28, v170
	ds_read_b128 v[110:113], v190
	ds_read_b128 v[122:125], v193
	ds_read2_b64 v[126:129], v70 offset0:96 offset1:100
	v_add_u32_e32 v70, 0xa800, v176
	v_add_u32_e32 v192, s28, v171
	ds_read2_b64 v[196:199], v70 offset0:128 offset1:132
	v_add_u32_e32 v70, 0xb000, v176
	v_add_u32_e32 v194, s28, v172
	ds_read_b128 v[200:203], v192
	ds_read_b128 v[204:207], v194
	ds_read2_b64 v[208:211], v70 offset0:160 offset1:164
	s_waitcnt lgkmcnt(10)
	v_pk_mul_f32 v[86:87], v[10:11], v[86:87]
	v_pk_mul_f32 v[88:89], v[12:13], v[88:89]
	v_add_u32_e32 v70, 0xb800, v176
	v_add_u32_e32 v184, s28, v173
	v_mfma_f32_16x16x32_bf16 v[98:101], v[82:85], v[74:77], v[86:89]
	s_waitcnt lgkmcnt(9)
	v_pk_mul_f32 v[82:83], v[38:39], v[90:91]
	v_pk_mul_f32 v[84:85], v[40:41], v[92:93]
	ds_read2_b64 v[90:93], v70 offset0:192 offset1:196
	v_add_u32_e32 v70, 0xc000, v176
	s_waitcnt lgkmcnt(9)
	v_mfma_f32_16x16x32_bf16 v[106:109], v[94:97], v[74:77], v[82:85]
	ds_read2_b64 v[94:97], v70 offset0:224 offset1:228
	v_add_u32_e32 v188, s28, v174
	ds_read_b128 v[212:215], v184
	s_waitcnt lgkmcnt(9)
	v_pk_mul_f32 v[82:83], v[42:43], v[110:111]
	v_pk_mul_f32 v[84:85], v[44:45], v[112:113]
	v_mov_b32_e32 v117, v71
	v_mov_b32_e32 v70, v80
	v_mfma_f32_16x16x32_bf16 v[110:113], v[102:105], v[74:77], v[82:85]
	v_mov_b32_e32 v71, v81
	v_cvt_pk_bf16_f32 v42, v42, v43
	v_cvt_pk_bf16_f32 v43, v44, v45
	s_waitcnt lgkmcnt(8)
	v_pk_mul_f32 v[82:83], v[46:47], v[122:123]
	v_pk_mul_f32 v[84:85], v[48:49], v[124:125]
	ds_read_b128 v[122:125], v188
	v_cvt_pk_bf16_f32 v44, v46, v47
	s_waitcnt lgkmcnt(8)
	v_mfma_f32_16x16x32_bf16 v[102:105], v[126:129], v[74:77], v[82:85]
	s_waitcnt lgkmcnt(1)
	v_pk_mul_f32 v[126:127], v[62:63], v[212:213]
	v_pk_mul_f32 v[128:129], v[64:65], v[214:215]
	s_waitcnt lgkmcnt(0)
	v_pk_mul_f32 v[122:123], v[58:59], v[122:123]
	v_pk_mul_f32 v[124:125], v[60:61], v[124:125]
	v_mfma_f32_16x16x32_bf16 v[90:93], v[90:93], v[74:77], v[126:129]
	v_cvt_pk_bf16_f32 v45, v48, v49
	v_mov_b32_e32 v114, v78
	v_mov_b32_e32 v115, v79
	v_mfma_f32_16x16x32_bf16 v[94:97], v[94:97], v[74:77], v[122:125]
	ds_read2_b64 v[126:129], v157 offset0:8 offset1:12
	v_pk_mul_f32 v[82:83], v[50:51], v[200:201]
	v_pk_mul_f32 v[84:85], v[52:53], v[202:203]
	v_add_u32_e32 v122, 0x1000, v157
	v_mfma_f32_16x16x32_bf16 v[46:49], v[74:77], v[70:73], 0
	ds_read2_b64 v[70:73], v122 offset0:40 offset1:44
	v_pk_mul_f32 v[86:87], v[54:55], v[204:205]
	v_pk_mul_f32 v[88:89], v[56:57], v[206:207]
	v_mfma_f32_16x16x32_bf16 v[82:85], v[196:199], v[74:77], v[82:85]
	v_cvt_pk_bf16_f32 v10, v10, v11
	v_cvt_pk_bf16_f32 v11, v12, v13
	v_cvt_pk_bf16_f32 v12, v38, v39
	v_mfma_f32_16x16x32_bf16 v[86:89], v[208:211], v[74:77], v[86:89]
	v_cvt_pk_bf16_f32 v13, v40, v41
	v_cvt_pk_bf16_f32 v62, v62, v63
	v_cvt_pk_bf16_f32 v63, v64, v65
	v_mfma_f32_16x16x32_bf16 v[78:81], v[74:77], v[114:117], 0
	v_cvt_pk_bf16_f32 v64, v58, v59
	v_cvt_pk_bf16_f32 v65, v60, v61
	v_cvt_pk_bf16_f32 v50, v50, v51
	s_waitcnt lgkmcnt(1)
	v_mfma_f32_16x16x32_bf16 v[74:77], v[42:45], v[126:129], 0
	v_cvt_pk_bf16_f32 v51, v52, v53
	v_cvt_pk_bf16_f32 v52, v54, v55
	v_cvt_pk_bf16_f32 v53, v56, v57
	s_waitcnt lgkmcnt(0)
	v_mfma_f32_16x16x32_bf16 v[38:41], v[42:45], v[70:73], 0
	ds_read2_b64 v[42:45], v157 offset0:24 offset1:28
	ds_read2_b64 v[70:73], v122 offset0:32 offset1:36
	v_add_u32_e32 v195, v161, v175
	v_add_u32_e32 v196, s34, v166
	v_mfma_f32_16x16x32_bf16 v[114:117], v[10:13], v[66:69], v[78:81]
	v_add_u32_e32 v183, 0x9000, v156
	v_add_u32_e32 v198, s34, v168
	v_add_u32_e32 v197, s34, v169
	s_waitcnt lgkmcnt(0)
	v_mfma_f32_16x16x32_bf16 v[10:13], v[10:13], v[70:73], v[46:49]
	s_nop 2
	ds_read2_b64 v[46:49], v157 offset0:16 offset1:20
	ds_read2_b64 v[58:61], v122 offset0:56 offset1:60
	global_load_dwordx4 v[66:69], v[118:119], off
	global_load_dwordx4 v[78:81], v[120:121], off
	ds_read2_b64 v[54:57], v122 offset0:48 offset1:52
	v_mfma_f32_16x16x32_bf16 v[42:45], v[62:65], v[42:45], v[74:77]
	v_add_u32_e32 v199, s34, v170
	v_cvt_pk_bf16_f32 v232, v98, v99
	v_cvt_pk_bf16_f32 v233, v100, v101
	s_waitcnt lgkmcnt(1)
	v_mfma_f32_16x16x32_bf16 v[38:41], v[62:65], v[58:61], v[38:41]
	v_lshl_add_u64 v[58:59], s[70:71], 0, v[138:139]
	v_lshl_add_u64 v[60:61], s[70:71], 0, v[136:137]
	global_load_dwordx4 v[74:77], v[58:59], off
	global_load_dwordx4 v[70:73], v[60:61], off
	v_add_u32_e32 v237, 4, v237
	global_load_dword v236, v237, s[70:71] sc1
	v_mfma_f32_16x16x32_bf16 v[46:49], v[50:53], v[46:49], v[114:117]
	v_cvt_pk_bf16_f32 v234, v106, v107
	v_cvt_pk_bf16_f32 v235, v108, v109
	v_add_u32_e32 v186, 0xa800, v156
	s_waitcnt lgkmcnt(0)
	v_mfma_f32_16x16x32_bf16 v[10:13], v[50:53], v[54:57], v[10:13]
	s_add_i32 s31, s31, -1
	s_nop 1
	v_pk_add_f32 v[44:45], v[44:45], v[48:49]
	v_pk_add_f32 v[42:43], v[42:43], v[46:47]
	ds_write_b128 v159, v[42:45]
	v_lshl_add_u64 v[136:137], v[136:137], 0, s[12:13]
	s_nop 0
	v_pk_add_f32 v[12:13], v[40:41], v[12:13]
	v_pk_add_f32 v[10:11], v[38:39], v[10:11]
	ds_write_b128 v159, v[10:13] offset:8448
	ds_read2st64_b64 v[10:13], v160 offset0:38 offset1:39
	ds_read2st64_b64 v[54:57], v160 offset0:40 offset1:41
	v_add_u32_e32 v38, 0xd000, v195
	ds_read2_b64 v[58:61], v38 offset1:4
	ds_read2_b64 v[50:53], v158 offset1:4
	ds_read2_b64 v[118:121], v158 offset0:8 offset1:12
	ds_read2_b64 v[46:49], v158 offset0:16 offset1:20
	ds_read2_b64 v[114:117], v158 offset0:24 offset1:28
	s_waitcnt lgkmcnt(6)
	v_mov_b32_e32 v62, v10
	v_add_u32_e32 v10, 0x3000, v157
	ds_read2_b64 v[126:129], v10 offset0:96 offset1:100
	ds_read2_b64 v[200:203], v10 offset0:104 offset1:108
	ds_read2_b64 v[122:125], v10 offset0:112 offset1:116
	ds_read2_b64 v[204:207], v10 offset0:120 offset1:124
	v_add_u32_e32 v10, 0x8800, v156
	v_mov_b32_e32 v63, v11
	s_waitcnt lgkmcnt(9)
	v_mov_b32_e32 v64, v54
	v_mov_b32_e32 v65, v55
	v_mov_b32_e32 v54, v12
	v_mov_b32_e32 v55, v13
	ds_read2_b64 v[10:13], v10 offset1:4
	ds_read_b128 v[38:41], v196
	ds_read_b128 v[42:45], v198
	ds_read2_b64 v[208:211], v183 offset0:32 offset1:36
	v_add_u32_e32 v183, 0x9800, v156
	ds_read2_b64 v[212:215], v183 offset0:64 offset1:68
	ds_read_b128 v[216:219], v197
	ds_read_b128 v[220:223], v199
	s_waitcnt lgkmcnt(5)
	v_pk_mul_f32 v[40:41], v[100:101], v[40:41]
	v_pk_mul_f32 v[38:39], v[98:99], v[38:39]
	v_mfma_f32_16x16x32_bf16 v[54:57], v[58:61], v[54:57], 0
	v_add_u32_e32 v183, 0xa000, v156
	ds_read2_b64 v[224:227], v183 offset0:96 offset1:100
	v_add_u32_e32 v183, s34, v171
	v_mfma_f32_16x16x32_bf16 v[10:13], v[10:13], v[58:61], v[38:41]
	v_add_u32_e32 v98, s34, v173
	v_add_u32_e32 v99, 0xb800, v156
	v_add_u32_e32 v100, 0xc000, v156
	s_waitcnt lgkmcnt(5)
	v_pk_mul_f32 v[40:41], v[108:109], v[44:45]
	v_pk_mul_f32 v[38:39], v[106:107], v[42:43]
	s_waitcnt lgkmcnt(2)
	v_pk_mul_f32 v[44:45], v[112:113], v[218:219]
	v_pk_mul_f32 v[42:43], v[110:111], v[216:217]
	v_cvt_pk_bf16_f32 v110, v110, v111
	v_cvt_pk_bf16_f32 v111, v112, v113
	v_cvt_pk_bf16_f32 v112, v102, v103
	v_cvt_pk_bf16_f32 v113, v104, v105
	v_mfma_f32_16x16x32_bf16 v[62:65], v[58:61], v[62:65], 0
	v_add_u32_e32 v216, 0xb000, v156
	ds_read2_b64 v[228:231], v186 offset0:128 offset1:132
	v_add_u32_e32 v186, s34, v172
	v_mfma_f32_16x16x32_bf16 v[118:121], v[110:113], v[118:121], 0
	v_lshl_add_u64 v[138:139], v[138:139], 0, s[22:23]
	v_lshl_add_u64 v[140:141], v[140:141], 0, s[24:25]
	s_cmp_eq_u32 s31, 0
	v_mfma_f32_16x16x32_bf16 v[106:109], v[110:113], v[200:203], 0
	v_cvt_pk_bf16_f32 v110, v90, v91
	v_cvt_pk_bf16_f32 v111, v92, v93
	v_cvt_pk_bf16_f32 v112, v94, v95
	v_cvt_pk_bf16_f32 v113, v96, v97
	v_mfma_f32_16x16x32_bf16 v[54:57], v[232:235], v[126:129], v[54:57]
	v_cvt_pk_bf16_f32 v126, v82, v83
	v_cvt_pk_bf16_f32 v127, v84, v85
	v_cvt_pk_bf16_f32 v128, v86, v87
	v_cvt_pk_bf16_f32 v129, v88, v89
	v_mfma_f32_16x16x32_bf16 v[50:53], v[232:235], v[50:53], v[62:65]
	v_lshl_add_u64 v[144:145], v[144:145], 0, s[26:27]
	v_mfma_f32_16x16x32_bf16 v[114:117], v[110:113], v[114:117], v[118:121]
	v_mfma_f32_16x16x32_bf16 v[46:49], v[126:129], v[46:49], v[50:53]
	v_mfma_f32_16x16x32_bf16 v[106:109], v[110:113], v[204:207], v[106:109]
	s_waitcnt lgkmcnt(2)
	s_nop 2
	v_pk_mul_f32 v[52:53], v[104:105], v[222:223]
	s_nop 1
	v_pk_add_f32 v[48:49], v[116:117], v[48:49]
	v_pk_add_f32 v[46:47], v[114:115], v[46:47]
	v_mfma_f32_16x16x32_bf16 v[54:57], v[126:129], v[122:125], v[54:57]
	v_mul_f32_e64 v50, v102, v220
	v_mul_f32_e64 v51, v103, v221
	v_mfma_f32_16x16x32_bf16 v[38:41], v[208:211], v[58:61], v[38:41]
	v_mfma_f32_16x16x32_bf16 v[42:45], v[212:215], v[58:61], v[42:45]
	ds_read_b128 v[208:211], v183
	ds_read_b128 v[212:215], v186
	ds_read2_b64 v[216:219], v216 offset0:160 offset1:164
	ds_read2_b64 v[62:65], v99 offset0:192 offset1:196
	v_add_u32_e32 v99, s34, v174
	ds_read_b128 v[110:113], v98
	ds_read_b128 v[118:121], v99
	ds_read2_b64 v[200:203], v100 offset0:224 offset1:228
	ds_write_b128 v155, v[46:49]
	v_pk_add_f32 v[48:49], v[108:109], v[56:57]
	v_pk_add_f32 v[46:47], v[106:107], v[54:55]
	ds_write_b128 v155, v[46:49] offset:8448
	s_waitcnt lgkmcnt(0)
	s_barrier
	ds_read_b128 v[104:107], v154
	ds_read_b128 v[114:117], v154 offset:16
	ds_read_b128 v[122:125], v154 offset:32
	ds_read_b128 v[126:129], v154 offset:48
	s_waitcnt lgkmcnt(14)
	v_mfma_f32_16x16x32_bf16 v[46:49], v[224:227], v[58:61], v[50:53]
	s_waitcnt lgkmcnt(3)
	s_nop 1
	v_pk_mul_f32 v[50:51], v[106:107], v[106:107]
	v_pk_mul_f32 v[52:53], v[104:105], v[104:105]
	s_nop 0
	v_pk_mov_b32 v[54:55], v[52:53], v[50:51] op_sel:[1,0]
	v_mov_b32_e32 v53, v51
	v_pk_add_f32 v[50:51], v[54:55], v[52:53]
	s_waitcnt lgkmcnt(2)
	v_pk_mul_f32 v[52:53], v[116:117], v[116:117]
	v_pk_mul_f32 v[54:55], v[114:115], v[114:115]
	v_pk_add_f32 v[50:51], v[50:51], v[50:51] op_sel:[0,1] op_sel_hi:[1,0]
	v_pk_mov_b32 v[56:57], v[54:55], v[52:53] op_sel:[1,0]
	v_mov_b32_e32 v55, v53
	v_pk_add_f32 v[52:53], v[56:57], v[54:55]
	s_waitcnt lgkmcnt(0)
	v_mul_f32_e32 v54, v126, v126
	v_mul_f32_e32 v55, v127, v127
	v_pk_add_f32 v[52:53], v[52:53], v[52:53] op_sel:[0,1] op_sel_hi:[1,0]
	v_mov_b32_e32 v51, v54
	v_mov_b32_e32 v53, v55
	v_pk_add_f32 v[50:51], v[50:51], v[52:53]
	v_mul_f32_e32 v52, v123, v123
	v_mul_f32_e32 v54, v125, v125
	v_mul_f32_e32 v56, v128, v128
	v_mul_f32_e32 v57, v129, v129
	v_pk_fma_f32 v[52:53], v[122:123], v[122:123], v[52:53] op_sel_hi:[1,1,0]
	v_pk_fma_f32 v[54:55], v[124:125], v[124:125], v[54:55] op_sel_hi:[1,1,0]
	v_mov_b32_e32 v53, v56
	v_mov_b32_e32 v55, v57
	v_pk_add_f32 v[52:53], v[52:53], v[54:55]
	v_pk_mul_f32 v[56:57], v[88:89], v[214:215]
	v_pk_add_f32 v[50:51], v[50:51], v[52:53]
	v_pk_mul_f32 v[52:53], v[84:85], v[210:211]
	v_add_f32_e32 v54, v50, v51
	v_and_b32_e32 v51, 64, v177
	v_xor_b32_e32 v50, 1, v177
	v_add_u32_e32 v102, 64, v51
	v_cmp_lt_i32_e32 vcc, v50, v102
	v_pk_mul_f32 v[84:85], v[92:93], v[112:113]
	v_add_u32_e32 v92, 0, v165
	v_cndmask_b32_e32 v50, v177, v50, vcc
	v_lshlrev_b32_e32 v100, 2, v50
	ds_bpermute_b32 v55, v100, v54
	v_pk_mul_f32 v[50:51], v[82:83], v[208:209]
	s_waitcnt lgkmcnt(0)
	v_add_f32_e32 v82, v54, v55
	v_xor_b32_e32 v54, 2, v177
	v_cmp_lt_i32_e32 vcc, v54, v102
	v_mfma_f32_16x16x32_bf16 v[50:53], v[228:231], v[58:61], v[50:53]
	s_nop 0
	v_cndmask_b32_e32 v54, v177, v54, vcc
	v_lshlrev_b32_e32 v101, 2, v54
	ds_bpermute_b32 v83, v101, v82
	v_pk_mul_f32 v[54:55], v[86:87], v[212:213]
	s_waitcnt lgkmcnt(0)
	v_add_f32_e32 v86, v82, v83
	v_xor_b32_e32 v82, 4, v177
	v_cmp_lt_i32_e32 vcc, v82, v102
	v_mfma_f32_16x16x32_bf16 v[54:57], v[216:219], v[58:61], v[54:57]
	s_nop 0
	v_cndmask_b32_e32 v82, v177, v82, vcc
	v_lshlrev_b32_e32 v102, 2, v82
	ds_bpermute_b32 v87, v102, v86
	v_pk_mul_f32 v[82:83], v[90:91], v[110:111]
	s_nop 1
	v_mfma_f32_16x16x32_bf16 v[62:65], v[62:65], v[58:61], v[82:85]
	s_waitcnt lgkmcnt(0)
	s_nop 1
	v_add_f32_e32 v82, v86, v87
	v_fmamk_f32 v82, v82, 0x3c000000, v178
	v_mul_f32_e32 v83, 0x4b800000, v82
	v_cmp_gt_f32_e32 vcc, s35, v82
	v_pk_mul_f32 v[84:85], v[96:97], v[120:121]
	s_nop 0
	v_cndmask_b32_e32 v82, v82, v83, vcc
	v_rsq_f32_e32 v86, v82
	v_pk_mul_f32 v[82:83], v[94:95], v[118:119]
	s_nop 1
	v_mfma_f32_16x16x32_bf16 v[58:61], v[200:203], v[58:61], v[82:85]
	s_nop 2
	v_mul_f32_e32 v82, 0x45800000, v86
	v_cndmask_b32_e32 v90, v86, v82, vcc
	v_pk_mul_f32 v[108:109], v[104:105], v[90:91] op_sel_hi:[1,0]
	v_add_u32_e32 v91, 0x1a000, v92
	ds_read_b128 v[82:85], v91
	v_pk_mul_f32 v[110:111], v[106:107], v[90:91] op_sel_hi:[1,0]
	ds_read_b128 v[86:89], v91 offset:16
	ds_read_b128 v[94:97], v91 offset:32
	ds_read_b128 v[104:107], v91 offset:48
	s_waitcnt lgkmcnt(3)
	v_pk_mul_f32 v[82:83], v[82:83], v[108:109]
	v_lshlrev_b32_e32 v108, 16, v26
	v_and_b32_e32 v109, 0xffff0000, v26
	v_pk_mul_f32 v[82:83], v[82:83], v[108:109]
	v_pk_mul_f32 v[84:85], v[84:85], v[110:111]
	v_cvt_pk_bf16_f32 v26, v82, v83
	v_lshlrev_b32_e32 v82, 16, v27
	v_and_b32_e32 v83, 0xffff0000, v27
	v_pk_mul_f32 v[82:83], v[84:85], v[82:83]
	v_pk_mul_f32 v[84:85], v[116:117], v[90:91] op_sel_hi:[1,0]
	v_cvt_pk_bf16_f32 v27, v82, v83
	v_pk_mul_f32 v[82:83], v[114:115], v[90:91] op_sel_hi:[1,0]
	s_waitcnt lgkmcnt(2)
	v_pk_mul_f32 v[84:85], v[88:89], v[84:85]
	v_pk_mul_f32 v[82:83], v[86:87], v[82:83]
	v_lshlrev_b32_e32 v86, 16, v28
	v_and_b32_e32 v87, 0xffff0000, v28
	v_pk_mul_f32 v[82:83], v[82:83], v[86:87]
	v_lshlrev_b32_e32 v86, 16, v14
	v_cvt_pk_bf16_f32 v28, v82, v83
	v_lshlrev_b32_e32 v82, 16, v29
	v_and_b32_e32 v83, 0xffff0000, v29
	v_pk_mul_f32 v[82:83], v[84:85], v[82:83]
	v_and_b32_e32 v87, 0xffff0000, v14
	v_cvt_pk_bf16_f32 v29, v82, v83
	v_pk_mul_f32 v[82:83], v[122:123], v[90:91] op_sel_hi:[1,0]
	v_pk_mul_f32 v[84:85], v[124:125], v[90:91] op_sel_hi:[1,0]
	s_waitcnt lgkmcnt(1)
	v_pk_mul_f32 v[82:83], v[94:95], v[82:83]
	v_pk_mul_f32 v[84:85], v[96:97], v[84:85]
	v_pk_mul_f32 v[82:83], v[82:83], v[86:87]
	v_lshlrev_b32_e32 v86, 16, v16
	v_cvt_pk_bf16_f32 v14, v82, v83
	v_lshlrev_b32_e32 v82, 16, v15
	v_and_b32_e32 v83, 0xffff0000, v15
	v_pk_mul_f32 v[82:83], v[84:85], v[82:83]
	v_and_b32_e32 v87, 0xffff0000, v16
	v_cvt_pk_bf16_f32 v15, v82, v83
	v_pk_mul_f32 v[82:83], v[126:127], v[90:91] op_sel_hi:[1,0]
	v_pk_mul_f32 v[84:85], v[128:129], v[90:91] op_sel_hi:[1,0]
	s_waitcnt lgkmcnt(0)
	v_pk_mul_f32 v[82:83], v[104:105], v[82:83]
	v_pk_mul_f32 v[84:85], v[106:107], v[84:85]
	v_pk_mul_f32 v[82:83], v[82:83], v[86:87]
	s_nop 0
	v_cvt_pk_bf16_f32 v16, v82, v83
	v_lshlrev_b32_e32 v82, 16, v17
	v_and_b32_e32 v83, 0xffff0000, v17
	v_pk_mul_f32 v[82:83], v[84:85], v[82:83]
	s_nop 0
	v_cvt_pk_bf16_f32 v17, v82, v83
	v_add_co_u32_e32 v82, vcc, s36, v146
	s_nop 1
	v_addc_co_u32_e32 v83, vcc, 0, v147, vcc
	global_store_dwordx4 v[82:83], v[26:29], off
	global_store_dwordx4 v[82:83], v[14:17], off offset:16
	s_cbranch_scc1 .LBB0_356
	s_waitcnt vmcnt(11)
	v_mov_b64_e32 v[28:29], v[8:9]
	s_waitcnt vmcnt(10)
	v_mov_b64_e32 v[16:17], v[4:5]
	v_mov_b64_e32 v[26:27], v[6:7]
	v_mov_b64_e32 v[14:15], v[2:3]
	s_branch .LBB0_350
